# k32: attention K/V LDS-DMA of each step issued after the ninth P.V MFMA (LDS-read-free gaps) instead of between QK^T and the row-max chain
# baseline (speedup 1.0000x reference)
.LBB0_1332:
	ds_read_b64_tr_b16 v[208:209], v243 offset:24576
	ds_read_b64_tr_b16 v[210:211], v243 offset:25088
	s_waitcnt lgkmcnt(9)
	v_mfma_f32_32x32x16_bf16 v[128:143], v[204:207], v[172:175], v[64:79]
	v_add_f32_e32 v112, v96, v97
	v_add_f32_e32 v112, v98, v112
	v_add_f32_e32 v112, v99, v112
	v_add_f32_e32 v112, v100, v112
	v_add_f32_e32 v112, v101, v112
	v_cvt_pk_bf16_f32 v164, v96, v97
	v_cvt_pk_bf16_f32 v165, v98, v99
	ds_read_b64_tr_b16 v[96:97], v243 offset:28672
	ds_read_b64_tr_b16 v[98:99], v243 offset:29184
	v_add_f32_e32 v112, v102, v112
	v_add_f32_e32 v112, v103, v112
	v_add_f32_e32 v112, v104, v112
	v_add_f32_e32 v144, v105, v112
	s_waitcnt lgkmcnt(10)
	v_mfma_f32_32x32x16_bf16 v[112:127], v[200:203], v[172:175], v[64:79]
	v_cvt_pk_bf16_f32 v166, v100, v101
	v_cvt_pk_bf16_f32 v167, v102, v103
	ds_read_b64_tr_b16 v[100:101], v243 offset:25600
	ds_read_b64_tr_b16 v[102:103], v243 offset:26112
	s_waitcnt lgkmcnt(11)
	v_mfma_f32_32x32x16_bf16 v[128:143], v[196:199], v[168:171], v[128:143]
	v_add_f32_e32 v144, v106, v144
	v_add_f32_e32 v144, v107, v144
	v_add_f32_e32 v144, v108, v144
	v_add_f32_e32 v144, v109, v144
	v_cvt_pk_bf16_f32 v156, v104, v105
	v_cvt_pk_bf16_f32 v157, v106, v107
	ds_read_b64_tr_b16 v[104:105], v243 offset:29696
	ds_read_b64_tr_b16 v[106:107], v243 offset:30208
	s_waitcnt lgkmcnt(12)
	v_mfma_f32_32x32x16_bf16 v[112:127], v[192:195], v[168:171], v[112:127]
	v_add_f32_e32 v144, v110, v144
	v_add_f32_e32 v144, v111, v144
	v_add_f32_e32 v144, v80, v144
	v_add_f32_e32 v144, v81, v144
	v_cvt_pk_bf16_f32 v158, v108, v109
	v_cvt_pk_bf16_f32 v159, v110, v111
	ds_read_b64_tr_b16 v[108:109], v243 offset:26624
	ds_read_b64_tr_b16 v[110:111], v243 offset:27136
	s_waitcnt lgkmcnt(13)
	v_mfma_f32_32x32x16_bf16 v[128:143], v[188:191], v[160:163], v[128:143]
	v_add_f32_e32 v144, v82, v144
	v_add_f32_e32 v144, v83, v144
	v_add_f32_e32 v144, v84, v144
	v_add_f32_e32 v144, v85, v144
	v_cvt_pk_bf16_f32 v148, v80, v81
	v_cvt_pk_bf16_f32 v149, v82, v83
	ds_read_b64_tr_b16 v[80:81], v243 offset:30720
	ds_read_b64_tr_b16 v[82:83], v243 offset:31232
	s_waitcnt lgkmcnt(14)
	v_mfma_f32_32x32x16_bf16 v[112:127], v[184:187], v[160:163], v[112:127]
	v_add_f32_e32 v144, v86, v144
	v_add_f32_e32 v144, v87, v144
	v_add_f32_e32 v144, v88, v144
	v_add_f32_e32 v144, v89, v144
	v_cvt_pk_bf16_f32 v150, v84, v85
	v_cvt_pk_bf16_f32 v151, v86, v87
	ds_read_b64_tr_b16 v[84:85], v243 offset:27648
	ds_read_b64_tr_b16 v[86:87], v243 offset:28160
	s_waitcnt lgkmcnt(14)
	v_mfma_f32_32x32x16_bf16 v[128:143], v[180:183], v[152:155], v[128:143]
	v_add_f32_e32 v144, v90, v144
	v_add_f32_e32 v144, v91, v144
	v_add_f32_e32 v144, v92, v144
	v_add_f32_e32 v184, v93, v144
	v_cvt_pk_bf16_f32 v144, v88, v89
	v_cvt_pk_bf16_f32 v145, v90, v91
	ds_read_b64_tr_b16 v[88:89], v243 offset:31744
	ds_read_b64_tr_b16 v[90:91], v243 offset:32256
	v_mfma_f32_32x32x16_bf16 v[112:127], v[176:179], v[152:155], v[112:127]
	v_add_f32_e32 v146, v94, v184
	v_add_f32_e32 v146, v95, v146
	v_add_f32_e32 v241, v241, v146
	v_cvt_pk_bf16_f32 v146, v92, v93
	v_cvt_pk_bf16_f32 v147, v94, v95
	v_max_f32_e32 v92, v128, v129
	s_nop 5
	v_max3_f32 v93, v130, v131, v113
	v_max3_f32 v92, v92, v112, v114
	v_max3_f32 v92, v92, v115, v132
	v_max3_f32 v93, v93, v134, v135
	v_max3_f32 v92, v92, v133, v116
	v_max3_f32 v93, v93, v118, v119
	v_max3_f32 v92, v92, v117, v136
	v_max3_f32 v93, v93, v138, v139
	v_max3_f32 v92, v92, v137, v120
	v_max3_f32 v93, v93, v122, v123
	v_max3_f32 v92, v92, v121, v140
	v_max3_f32 v93, v93, v142, v143
	v_max3_f32 v92, v92, v141, v124
	v_max3_f32 v93, v93, v126, v127
	v_max3_f32 v92, v92, v125, v93
	v_mov_b32_e32 v93, v92
	s_nop 1
	v_permlane32_swap_b32_e32 v92, v93
	v_max_f32_e32 v92, v92, v93
	v_cmp_lt_f32_e32 vcc, s41, v92
	s_cmp_lg_u64 vcc, 0
	s_cselect_b64 s[36:37], -1, 0
	s_cbranch_vccnz .LBB0_1340
.LBB0_1333:
	s_waitcnt lgkmcnt(14)
	v_mfma_f32_32x32x16_bf16 v[48:63], v[164:167], v[208:211], v[48:63]
	v_exp_f32_e32 v128, v128
	v_exp_f32_e32 v129, v129
	ds_read_b64_tr_b16 v[92:93], v243 offset:32768
	ds_read_b64_tr_b16 v[94:95], v243 offset:33280
	s_waitcnt lgkmcnt(14)
	v_mfma_f32_32x32x16_bf16 v[32:47], v[164:167], v[96:99], v[32:47]
	v_exp_f32_e32 v130, v130
	v_exp_f32_e32 v131, v131
	ds_read_b64_tr_b16 v[96:97], v243 offset:36864
	ds_read_b64_tr_b16 v[98:99], v243 offset:37376
	s_waitcnt lgkmcnt(14)
	v_mfma_f32_32x32x16_bf16 v[48:63], v[156:159], v[100:103], v[48:63]
	v_exp_f32_e32 v132, v132
	v_exp_f32_e32 v133, v133
	ds_read_b64_tr_b16 v[100:101], v243 offset:33792
	ds_read_b64_tr_b16 v[102:103], v243 offset:34304
	s_waitcnt lgkmcnt(14)
	v_mfma_f32_32x32x16_bf16 v[32:47], v[156:159], v[104:107], v[32:47]
	v_exp_f32_e32 v134, v134
	v_exp_f32_e32 v135, v135
	ds_read_b64_tr_b16 v[104:105], v243 offset:37888
	ds_read_b64_tr_b16 v[106:107], v243 offset:38400
	s_waitcnt lgkmcnt(14)
	v_mfma_f32_32x32x16_bf16 v[48:63], v[148:151], v[108:111], v[48:63]
	v_exp_f32_e32 v136, v136
	v_exp_f32_e32 v137, v137
	ds_read_b64_tr_b16 v[108:109], v243 offset:34816
	ds_read_b64_tr_b16 v[110:111], v243 offset:35328
	s_waitcnt lgkmcnt(14)
	v_mfma_f32_32x32x16_bf16 v[32:47], v[148:151], v[80:83], v[32:47]
	v_exp_f32_e32 v138, v138
	v_exp_f32_e32 v139, v139
	ds_read_b64_tr_b16 v[196:197], v243 offset:38912
	ds_read_b64_tr_b16 v[198:199], v243 offset:39424
	s_waitcnt lgkmcnt(14)
	v_mfma_f32_32x32x16_bf16 v[48:63], v[144:147], v[84:87], v[48:63]
	v_exp_f32_e32 v140, v140
	v_exp_f32_e32 v141, v141
	ds_read_b64_tr_b16 v[84:85], v243 offset:35840
	ds_read_b64_tr_b16 v[86:87], v243 offset:36352
	s_waitcnt lgkmcnt(14)
	v_mfma_f32_32x32x16_bf16 v[32:47], v[144:147], v[88:91], v[32:47]
	v_exp_f32_e32 v142, v142
	v_exp_f32_e32 v143, v143
	ds_read_b64_tr_b16 v[88:89], v243 offset:39936
	ds_read_b64_tr_b16 v[90:91], v243 offset:40448
	s_waitcnt lgkmcnt(14)
	v_mfma_f32_32x32x16_bf16 v[16:31], v[164:167], v[92:95], v[16:31]
	s_add_i32 s4, s11, s76
	s_mov_b32 m0, s4
	s_nop 0
	global_load_lds_dwordx4 v248, s[98:99]
	s_lshl_b32 s4, s38, 1
	s_add_i32 s4, s4, s77
	s_mov_b32 m0, s4
	s_nop 0
	global_load_lds_dwordx4 v250, s[100:101]
	s_addk_i32 s4, 0x2000
	s_mov_b32 m0, s4
	s_nop 0
	global_load_lds_dwordx4 v252, s[100:101]
	v_exp_f32_e32 v112, v112
	v_exp_f32_e32 v113, v113
	s_waitcnt lgkmcnt(12)
	v_mfma_f32_32x32x16_bf16 v[0:15], v[164:167], v[96:99], v[0:15]
	v_exp_f32_e32 v114, v114
	v_exp_f32_e32 v115, v115
	v_add_u32_e32 v92, s38, v238
	ds_read_b128 v[80:83], v92
	ds_read_b128 v[204:207], v92 offset:512
	s_waitcnt lgkmcnt(12)
	v_mfma_f32_32x32x16_bf16 v[16:31], v[156:159], v[100:103], v[16:31]
	v_exp_f32_e32 v116, v116
	v_exp_f32_e32 v117, v117
	ds_read_b128 v[200:203], v92 offset:2048
	ds_read_b128 v[192:195], v92 offset:2560
	s_waitcnt lgkmcnt(12)
	v_mfma_f32_32x32x16_bf16 v[0:15], v[156:159], v[104:107], v[0:15]
	v_exp_f32_e32 v118, v118
	v_exp_f32_e32 v119, v119
	ds_read_b128 v[188:191], v92 offset:4096
	ds_read_b128 v[184:187], v92 offset:4608
	s_waitcnt lgkmcnt(12)
	v_mfma_f32_32x32x16_bf16 v[16:31], v[148:151], v[108:111], v[16:31]
	v_exp_f32_e32 v120, v120
	v_exp_f32_e32 v121, v121
	ds_read_b128 v[180:183], v92 offset:6144
	ds_read_b128 v[176:179], v92 offset:6656
	s_waitcnt lgkmcnt(12)
	v_mfma_f32_32x32x16_bf16 v[0:15], v[148:151], v[196:199], v[0:15]
	v_exp_f32_e32 v122, v122
	v_exp_f32_e32 v123, v123
	s_waitcnt lgkmcnt(10)
	v_mfma_f32_32x32x16_bf16 v[16:31], v[144:147], v[84:87], v[16:31]
	v_exp_f32_e32 v124, v124
	v_exp_f32_e32 v125, v125
	s_waitcnt lgkmcnt(8)
	v_mfma_f32_32x32x16_bf16 v[0:15], v[144:147], v[88:91], v[0:15]
	v_exp_f32_e32 v126, v126
	v_exp_f32_e32 v127, v127
	s_add_i32 s4, s38, 0x2000
	s_cmpk_lg_i32 s38, 0x4000
	s_cselect_b32 s78, s4, 0
	s_lshl_b32 s4, s11, 1
	v_add_u32_e32 v209, s4, v239
	s_waitcnt vmcnt(3) lgkmcnt(0)
	s_barrier
	s_andn2_b64 vcc, exec, s[36:37]
	v_add_u32_e32 v208, s75, v240
	s_cbranch_vccnz .LBB0_1335
	s_waitcnt lgkmcnt(0)
	ds_read_b128 v[84:87], v208 offset:96
	ds_read_b128 v[88:91], v208 offset:64
	ds_read_b128 v[92:95], v208 offset:32
	ds_read_b128 v[96:99], v208
	s_waitcnt lgkmcnt(3)
	v_pk_mul_f32 v[60:61], v[60:61], v[84:85]
	s_waitcnt lgkmcnt(2)
	v_pk_mul_f32 v[56:57], v[56:57], v[88:89]
	s_waitcnt lgkmcnt(1)
	v_pk_mul_f32 v[52:53], v[52:53], v[92:93]
	v_pk_mul_f32 v[62:63], v[62:63], v[86:87]
	v_pk_mul_f32 v[58:59], v[58:59], v[90:91]
	v_pk_mul_f32 v[54:55], v[54:55], v[94:95]
	s_waitcnt lgkmcnt(0)
	v_pk_mul_f32 v[50:51], v[50:51], v[98:99]
	v_pk_mul_f32 v[48:49], v[48:49], v[96:97]
	v_pk_mul_f32 v[44:45], v[44:45], v[84:85]
	v_pk_mul_f32 v[40:41], v[40:41], v[88:89]
	v_pk_mul_f32 v[36:37], v[36:37], v[92:93]
	v_pk_mul_f32 v[46:47], v[46:47], v[86:87]
	v_pk_mul_f32 v[42:43], v[42:43], v[90:91]
	v_pk_mul_f32 v[38:39], v[38:39], v[94:95]
	v_pk_mul_f32 v[34:35], v[34:35], v[98:99]
	v_pk_mul_f32 v[32:33], v[32:33], v[96:97]
	v_pk_mul_f32 v[28:29], v[28:29], v[84:85]
	v_pk_mul_f32 v[24:25], v[24:25], v[88:89]
	v_pk_mul_f32 v[20:21], v[20:21], v[92:93]
	v_pk_mul_f32 v[30:31], v[30:31], v[86:87]
	v_pk_mul_f32 v[26:27], v[26:27], v[90:91]
	v_pk_mul_f32 v[22:23], v[22:23], v[94:95]
	v_pk_mul_f32 v[18:19], v[18:19], v[98:99]
	v_pk_mul_f32 v[16:17], v[16:17], v[96:97]
	v_pk_mul_f32 v[12:13], v[12:13], v[84:85]
	v_pk_mul_f32 v[8:9], v[8:9], v[88:89]
	v_pk_mul_f32 v[4:5], v[4:5], v[92:93]
	v_pk_mul_f32 v[14:15], v[14:15], v[86:87]
	v_pk_mul_f32 v[10:11], v[10:11], v[90:91]
	v_pk_mul_f32 v[6:7], v[6:7], v[94:95]
	v_pk_mul_f32 v[2:3], v[2:3], v[98:99]
	v_pk_mul_f32 v[0:1], v[0:1], v[96:97]
.LBB0_1335:
	ds_read_b64_tr_b16 v[196:197], v209 offset:24576
	ds_read_b64_tr_b16 v[198:199], v209 offset:25088
	s_waitcnt lgkmcnt(9)
	v_mfma_f32_32x32x16_bf16 v[96:111], v[80:83], v[172:175], v[64:79]
	v_add_f32_e32 v84, v128, v129
	v_add_f32_e32 v84, v130, v84
	v_add_f32_e32 v84, v131, v84
	v_add_f32_e32 v84, v132, v84
	v_add_f32_e32 v84, v133, v84
	v_cvt_pk_bf16_f32 v164, v128, v129
	v_cvt_pk_bf16_f32 v165, v130, v131
	ds_read_b64_tr_b16 v[128:129], v209 offset:28672
	ds_read_b64_tr_b16 v[130:131], v209 offset:29184
	v_add_f32_e32 v80, v134, v84
	v_add_f32_e32 v80, v135, v80
	v_add_f32_e32 v80, v136, v80
	v_add_f32_e32 v144, v137, v80
	s_waitcnt lgkmcnt(10)
	v_mfma_f32_32x32x16_bf16 v[80:95], v[204:207], v[172:175], v[64:79]
	v_cvt_pk_bf16_f32 v166, v132, v133
	v_cvt_pk_bf16_f32 v167, v134, v135
	ds_read_b64_tr_b16 v[132:133], v209 offset:25600
	ds_read_b64_tr_b16 v[134:135], v209 offset:26112
	s_waitcnt lgkmcnt(11)
	v_mfma_f32_32x32x16_bf16 v[96:111], v[200:203], v[168:171], v[96:111]
	v_add_f32_e32 v144, v138, v144
	v_add_f32_e32 v144, v139, v144
	v_add_f32_e32 v144, v140, v144
	v_add_f32_e32 v144, v141, v144
	v_cvt_pk_bf16_f32 v156, v136, v137
	v_cvt_pk_bf16_f32 v157, v138, v139
	ds_read_b64_tr_b16 v[136:137], v209 offset:29696
	ds_read_b64_tr_b16 v[138:139], v209 offset:30208
	s_waitcnt lgkmcnt(12)
	v_mfma_f32_32x32x16_bf16 v[80:95], v[192:195], v[168:171], v[80:95]
	v_add_f32_e32 v144, v142, v144
	v_add_f32_e32 v144, v143, v144
	v_add_f32_e32 v144, v112, v144
	v_add_f32_e32 v144, v113, v144
	v_cvt_pk_bf16_f32 v158, v140, v141
	v_cvt_pk_bf16_f32 v159, v142, v143
	ds_read_b64_tr_b16 v[140:141], v209 offset:26624
	ds_read_b64_tr_b16 v[142:143], v209 offset:27136
	s_waitcnt lgkmcnt(13)
	v_mfma_f32_32x32x16_bf16 v[96:111], v[188:191], v[160:163], v[96:111]
	v_add_f32_e32 v144, v114, v144
	v_add_f32_e32 v144, v115, v144
	v_add_f32_e32 v144, v116, v144
	v_add_f32_e32 v144, v117, v144
	v_cvt_pk_bf16_f32 v148, v112, v113
	v_cvt_pk_bf16_f32 v149, v114, v115
	ds_read_b64_tr_b16 v[112:113], v209 offset:30720
	ds_read_b64_tr_b16 v[114:115], v209 offset:31232
	s_waitcnt lgkmcnt(14)
	v_mfma_f32_32x32x16_bf16 v[80:95], v[184:187], v[160:163], v[80:95]
	v_add_f32_e32 v144, v118, v144
	v_add_f32_e32 v144, v119, v144
	v_add_f32_e32 v144, v120, v144
	v_add_f32_e32 v144, v121, v144
	v_cvt_pk_bf16_f32 v150, v116, v117
	v_cvt_pk_bf16_f32 v151, v118, v119
	ds_read_b64_tr_b16 v[116:117], v209 offset:27648
	ds_read_b64_tr_b16 v[118:119], v209 offset:28160
	s_waitcnt lgkmcnt(14)
	v_mfma_f32_32x32x16_bf16 v[96:111], v[180:183], v[152:155], v[96:111]
	v_add_f32_e32 v144, v122, v144
	v_add_f32_e32 v144, v123, v144
	v_add_f32_e32 v144, v124, v144
	v_add_f32_e32 v184, v125, v144
	v_cvt_pk_bf16_f32 v144, v120, v121
	v_cvt_pk_bf16_f32 v145, v122, v123
	ds_read_b64_tr_b16 v[120:121], v209 offset:31744
	ds_read_b64_tr_b16 v[122:123], v209 offset:32256
	v_mfma_f32_32x32x16_bf16 v[80:95], v[176:179], v[152:155], v[80:95]
	v_add_f32_e32 v146, v126, v184
	v_add_f32_e32 v146, v127, v146
	v_add_f32_e32 v241, v241, v146
	v_cvt_pk_bf16_f32 v146, v124, v125
	v_cvt_pk_bf16_f32 v147, v126, v127
	v_max_f32_e32 v124, v96, v97
	s_nop 3
	s_nop 1
	v_max3_f32 v125, v98, v99, v81
	v_max3_f32 v124, v124, v80, v82
	v_max3_f32 v124, v124, v83, v100
	v_max3_f32 v125, v125, v102, v103
	v_max3_f32 v124, v124, v101, v84
	v_max3_f32 v125, v125, v86, v87
	v_max3_f32 v124, v124, v85, v104
	v_max3_f32 v125, v125, v106, v107
	v_max3_f32 v124, v124, v105, v88
	v_max3_f32 v125, v125, v90, v91
	v_max3_f32 v124, v124, v89, v108
	v_max3_f32 v125, v125, v110, v111
	v_max3_f32 v124, v124, v109, v92
	v_max3_f32 v125, v125, v94, v95
	v_max3_f32 v124, v124, v93, v125
	v_mov_b32_e32 v125, v124
	s_nop 0
	s_nop 0
	v_permlane32_swap_b32_e32 v124, v125
	v_max_f32_e32 v124, v124, v125
	v_cmp_lt_f32_e32 vcc, s41, v124
	s_cmp_lg_u64 vcc, 0
	s_cselect_b64 s[36:37], -1, 0
	s_cbranch_vccnz .LBB0_1343
.LBB0_1336:
	s_waitcnt lgkmcnt(14)
	v_mfma_f32_32x32x16_bf16 v[48:63], v[164:167], v[196:199], v[48:63]
	v_exp_f32_e32 v96, v96
	v_exp_f32_e32 v97, v97
	ds_read_b64_tr_b16 v[124:125], v209 offset:32768
	ds_read_b64_tr_b16 v[126:127], v209 offset:33280
	s_waitcnt lgkmcnt(14)
	v_mfma_f32_32x32x16_bf16 v[32:47], v[164:167], v[128:131], v[32:47]
	v_exp_f32_e32 v98, v98
	v_exp_f32_e32 v99, v99
	ds_read_b64_tr_b16 v[128:129], v209 offset:36864
	ds_read_b64_tr_b16 v[130:131], v209 offset:37376
	s_waitcnt lgkmcnt(14)
	v_mfma_f32_32x32x16_bf16 v[48:63], v[156:159], v[132:135], v[48:63]
	v_exp_f32_e32 v100, v100
	v_exp_f32_e32 v101, v101
	ds_read_b64_tr_b16 v[132:133], v209 offset:33792
	ds_read_b64_tr_b16 v[134:135], v209 offset:34304
	s_waitcnt lgkmcnt(14)
	v_mfma_f32_32x32x16_bf16 v[32:47], v[156:159], v[136:139], v[32:47]
	v_exp_f32_e32 v102, v102
	v_exp_f32_e32 v103, v103
	ds_read_b64_tr_b16 v[136:137], v209 offset:37888
	ds_read_b64_tr_b16 v[138:139], v209 offset:38400
	s_waitcnt lgkmcnt(14)
	v_mfma_f32_32x32x16_bf16 v[48:63], v[148:151], v[140:143], v[48:63]
	v_exp_f32_e32 v104, v104
	v_exp_f32_e32 v105, v105
	ds_read_b64_tr_b16 v[140:141], v209 offset:34816
	ds_read_b64_tr_b16 v[142:143], v209 offset:35328
	s_waitcnt lgkmcnt(14)
	v_mfma_f32_32x32x16_bf16 v[32:47], v[148:151], v[112:115], v[32:47]
	v_exp_f32_e32 v106, v106
	v_exp_f32_e32 v107, v107
	ds_read_b64_tr_b16 v[112:113], v209 offset:38912
	ds_read_b64_tr_b16 v[114:115], v209 offset:39424
	s_waitcnt lgkmcnt(14)
	v_mfma_f32_32x32x16_bf16 v[48:63], v[144:147], v[116:119], v[48:63]
	v_exp_f32_e32 v108, v108
	v_exp_f32_e32 v109, v109
	ds_read_b64_tr_b16 v[116:117], v209 offset:35840
	ds_read_b64_tr_b16 v[118:119], v209 offset:36352
	s_waitcnt lgkmcnt(14)
	v_mfma_f32_32x32x16_bf16 v[32:47], v[144:147], v[120:123], v[32:47]
	v_exp_f32_e32 v110, v110
	v_exp_f32_e32 v111, v111
	ds_read_b64_tr_b16 v[120:121], v209 offset:39936
	ds_read_b64_tr_b16 v[122:123], v209 offset:40448
	s_waitcnt lgkmcnt(14)
	v_mfma_f32_32x32x16_bf16 v[16:31], v[164:167], v[124:127], v[16:31]
	s_add_i32 s4, s38, s76
	s_mov_b32 m0, s4
	s_nop 0
	global_load_lds_dwordx4 v249, s[98:99]
	s_lshl_b32 s4, s78, 1
	s_add_i32 s4, s4, s77
	s_mov_b32 m0, s4
	s_nop 0
	global_load_lds_dwordx4 v251, s[100:101]
	s_addk_i32 s4, 0x2000
	s_mov_b32 m0, s4
	s_nop 0
	global_load_lds_dwordx4 v253, s[100:101]
	v_exp_f32_e32 v80, v80
	v_exp_f32_e32 v81, v81
	s_waitcnt lgkmcnt(12)
	v_mfma_f32_32x32x16_bf16 v[0:15], v[164:167], v[128:131], v[0:15]
	v_exp_f32_e32 v82, v82
	v_exp_f32_e32 v83, v83
	v_add_u32_e32 v124, s78, v238
	ds_read_b128 v[204:207], v124
	ds_read_b128 v[200:203], v124 offset:512
	s_waitcnt lgkmcnt(12)
	v_mfma_f32_32x32x16_bf16 v[16:31], v[156:159], v[132:135], v[16:31]
	v_exp_f32_e32 v84, v84
	v_exp_f32_e32 v85, v85
	ds_read_b128 v[196:199], v124 offset:2048
	ds_read_b128 v[192:195], v124 offset:2560
	s_waitcnt lgkmcnt(12)
	v_mfma_f32_32x32x16_bf16 v[0:15], v[156:159], v[136:139], v[0:15]
	v_exp_f32_e32 v86, v86
	v_exp_f32_e32 v87, v87
	ds_read_b128 v[188:191], v124 offset:4096
	ds_read_b128 v[184:187], v124 offset:4608
	s_waitcnt lgkmcnt(12)
	v_mfma_f32_32x32x16_bf16 v[16:31], v[148:151], v[140:143], v[16:31]
	v_exp_f32_e32 v88, v88
	v_exp_f32_e32 v89, v89
	ds_read_b128 v[180:183], v124 offset:6144
	ds_read_b128 v[176:179], v124 offset:6656
	s_waitcnt lgkmcnt(12)
	v_mfma_f32_32x32x16_bf16 v[0:15], v[148:151], v[112:115], v[0:15]
	v_exp_f32_e32 v90, v90
	v_exp_f32_e32 v91, v91
	s_waitcnt lgkmcnt(10)
	v_mfma_f32_32x32x16_bf16 v[16:31], v[144:147], v[116:119], v[16:31]
	v_exp_f32_e32 v92, v92
	v_exp_f32_e32 v93, v93
	s_waitcnt lgkmcnt(8)
	v_mfma_f32_32x32x16_bf16 v[0:15], v[144:147], v[120:123], v[0:15]
	v_exp_f32_e32 v94, v94
	v_exp_f32_e32 v95, v95
	s_add_i32 s10, s10, 2
	s_add_i32 s4, s78, 0x2000
	s_cmpk_lg_i32 s78, 0x4000
	s_cselect_b32 s79, s4, 0
	s_add_u32 s98, s98, s16
	s_addc_u32 s99, s99, s17
	s_add_u32 s100, s100, s16
	s_addc_u32 s101, s101, s17
	s_lshl_b32 s4, s38, 1
	v_add_u32_e32 v243, s4, v239
	s_waitcnt vmcnt(3) lgkmcnt(0)
	s_barrier
	s_andn2_b64 vcc, exec, s[36:37]
	s_cbranch_vccnz .LBB0_1338
	s_waitcnt lgkmcnt(0)
	ds_read_b128 v[112:115], v208 offset:96
	ds_read_b128 v[116:119], v208 offset:64
	ds_read_b128 v[120:123], v208 offset:32
	ds_read_b128 v[124:127], v208
	s_waitcnt lgkmcnt(3)
	v_pk_mul_f32 v[60:61], v[60:61], v[112:113]
	s_waitcnt lgkmcnt(2)
	v_pk_mul_f32 v[56:57], v[56:57], v[116:117]
	s_waitcnt lgkmcnt(1)
	v_pk_mul_f32 v[52:53], v[52:53], v[120:121]
	v_pk_mul_f32 v[62:63], v[62:63], v[114:115]
	v_pk_mul_f32 v[58:59], v[58:59], v[118:119]
	v_pk_mul_f32 v[54:55], v[54:55], v[122:123]
	s_waitcnt lgkmcnt(0)
	v_pk_mul_f32 v[50:51], v[50:51], v[126:127]
	v_pk_mul_f32 v[48:49], v[48:49], v[124:125]
	v_pk_mul_f32 v[44:45], v[44:45], v[112:113]
	v_pk_mul_f32 v[40:41], v[40:41], v[116:117]
	v_pk_mul_f32 v[36:37], v[36:37], v[120:121]
	v_pk_mul_f32 v[46:47], v[46:47], v[114:115]
	v_pk_mul_f32 v[42:43], v[42:43], v[118:119]
	v_pk_mul_f32 v[38:39], v[38:39], v[122:123]
	v_pk_mul_f32 v[34:35], v[34:35], v[126:127]
	v_pk_mul_f32 v[32:33], v[32:33], v[124:125]
	v_pk_mul_f32 v[28:29], v[28:29], v[112:113]
	v_pk_mul_f32 v[24:25], v[24:25], v[116:117]
	v_pk_mul_f32 v[20:21], v[20:21], v[120:121]
	v_pk_mul_f32 v[30:31], v[30:31], v[114:115]
	v_pk_mul_f32 v[26:27], v[26:27], v[118:119]
	v_pk_mul_f32 v[22:23], v[22:23], v[122:123]
	v_pk_mul_f32 v[18:19], v[18:19], v[126:127]
	v_pk_mul_f32 v[16:17], v[16:17], v[124:125]
	v_pk_mul_f32 v[12:13], v[12:13], v[112:113]
	v_pk_mul_f32 v[8:9], v[8:9], v[116:117]
	v_pk_mul_f32 v[4:5], v[4:5], v[120:121]
	v_pk_mul_f32 v[14:15], v[14:15], v[114:115]
	v_pk_mul_f32 v[10:11], v[10:11], v[118:119]
	v_pk_mul_f32 v[6:7], v[6:7], v[122:123]
	v_pk_mul_f32 v[2:3], v[2:3], v[126:127]
	v_pk_mul_f32 v[0:1], v[0:1], v[124:125]

.LBB0_1359:
	ds_read_b64_tr_b16 v[208:209], v245 offset:24576
	ds_read_b64_tr_b16 v[210:211], v245 offset:25088
	s_waitcnt lgkmcnt(9)
	v_mfma_f32_32x32x16_bf16 v[128:143], v[204:207], v[172:175], v[64:79]
	v_add_f32_e32 v112, v96, v97
	v_add_f32_e32 v112, v98, v112
	v_add_f32_e32 v112, v99, v112
	v_add_f32_e32 v112, v100, v112
	v_add_f32_e32 v112, v101, v112
	v_cvt_pk_bf16_f32 v160, v96, v97
	v_cvt_pk_bf16_f32 v161, v98, v99
	ds_read_b64_tr_b16 v[96:97], v245 offset:28672
	ds_read_b64_tr_b16 v[98:99], v245 offset:29184
	v_add_f32_e32 v112, v102, v112
	v_add_f32_e32 v112, v103, v112
	v_add_f32_e32 v112, v104, v112
	v_add_f32_e32 v144, v105, v112
	s_waitcnt lgkmcnt(10)
	v_mfma_f32_32x32x16_bf16 v[112:127], v[200:203], v[172:175], v[64:79]
	v_cvt_pk_bf16_f32 v162, v100, v101
	v_cvt_pk_bf16_f32 v163, v102, v103
	ds_read_b64_tr_b16 v[100:101], v245 offset:25600
	ds_read_b64_tr_b16 v[102:103], v245 offset:26112
	s_waitcnt lgkmcnt(11)
	v_mfma_f32_32x32x16_bf16 v[128:143], v[196:199], v[168:171], v[128:143]
	v_add_f32_e32 v144, v106, v144
	v_add_f32_e32 v144, v107, v144
	v_add_f32_e32 v144, v108, v144
	v_add_f32_e32 v144, v109, v144
	v_cvt_pk_bf16_f32 v156, v104, v105
	v_cvt_pk_bf16_f32 v157, v106, v107
	ds_read_b64_tr_b16 v[104:105], v245 offset:29696
	ds_read_b64_tr_b16 v[106:107], v245 offset:30208
	s_waitcnt lgkmcnt(12)
	v_mfma_f32_32x32x16_bf16 v[112:127], v[192:195], v[168:171], v[112:127]
	v_add_f32_e32 v144, v110, v144
	v_add_f32_e32 v144, v111, v144
	v_add_f32_e32 v144, v80, v144
	v_add_f32_e32 v144, v81, v144
	v_cvt_pk_bf16_f32 v158, v108, v109
	v_cvt_pk_bf16_f32 v159, v110, v111
	ds_read_b64_tr_b16 v[108:109], v245 offset:26624
	ds_read_b64_tr_b16 v[110:111], v245 offset:27136
	s_waitcnt lgkmcnt(13)
	v_mfma_f32_32x32x16_bf16 v[128:143], v[188:191], v[164:167], v[128:143]
	v_add_f32_e32 v144, v82, v144
	v_add_f32_e32 v144, v83, v144
	v_add_f32_e32 v144, v84, v144
	v_add_f32_e32 v144, v85, v144
	v_cvt_pk_bf16_f32 v148, v80, v81
	v_cvt_pk_bf16_f32 v149, v82, v83
	ds_read_b64_tr_b16 v[80:81], v245 offset:30720
	ds_read_b64_tr_b16 v[82:83], v245 offset:31232
	s_waitcnt lgkmcnt(14)
	v_mfma_f32_32x32x16_bf16 v[112:127], v[184:187], v[164:167], v[112:127]
	v_add_f32_e32 v144, v86, v144
	v_add_f32_e32 v144, v87, v144
	v_add_f32_e32 v144, v88, v144
	v_add_f32_e32 v144, v89, v144
	v_cvt_pk_bf16_f32 v150, v84, v85
	v_cvt_pk_bf16_f32 v151, v86, v87
	ds_read_b64_tr_b16 v[84:85], v245 offset:27648
	ds_read_b64_tr_b16 v[86:87], v245 offset:28160
	s_waitcnt lgkmcnt(14)
	v_mfma_f32_32x32x16_bf16 v[128:143], v[180:183], v[152:155], v[128:143]
	v_add_f32_e32 v144, v90, v144
	v_add_f32_e32 v144, v91, v144
	v_add_f32_e32 v144, v92, v144
	v_add_f32_e32 v184, v93, v144
	v_cvt_pk_bf16_f32 v144, v88, v89
	v_cvt_pk_bf16_f32 v145, v90, v91
	ds_read_b64_tr_b16 v[88:89], v245 offset:31744
	ds_read_b64_tr_b16 v[90:91], v245 offset:32256
	v_mfma_f32_32x32x16_bf16 v[112:127], v[176:179], v[152:155], v[112:127]
	v_add_f32_e32 v146, v94, v184
	v_add_f32_e32 v146, v95, v146
	v_add_f32_e32 v180, 0, v146
	v_cvt_pk_bf16_f32 v146, v92, v93
	v_cvt_pk_bf16_f32 v147, v94, v95
	v_max_f32_e32 v92, v128, v129
	s_nop 5
	v_max3_f32 v93, v130, v131, v113
	v_max3_f32 v92, v92, v112, v114
	v_max3_f32 v92, v92, v115, v132
	v_max3_f32 v93, v93, v134, v135
	v_max3_f32 v92, v92, v133, v116
	v_max3_f32 v93, v93, v118, v119
	v_max3_f32 v92, v92, v117, v136
	v_max3_f32 v93, v93, v138, v139
	v_max3_f32 v92, v92, v137, v120
	v_max3_f32 v93, v93, v122, v123
	v_max3_f32 v92, v92, v121, v140
	v_max3_f32 v93, v93, v142, v143
	v_max3_f32 v92, v92, v141, v124
	v_max3_f32 v93, v93, v126, v127
	v_max3_f32 v92, v92, v125, v93
	v_mov_b32_e32 v93, v92
	s_nop 1
	v_permlane32_swap_b32_e32 v92, v93
	v_max_f32_e32 v92, v92, v93
	v_cmp_lt_f32_e32 vcc, s41, v92
	s_cmp_lg_u64 vcc, 0
	v_add_f32_e32 v233, v243, v180
	s_cselect_b64 s[10:11], -1, 0
	s_cbranch_vccnz .LBB0_1367
.LBB0_1360:
	s_waitcnt lgkmcnt(14)
	v_mfma_f32_32x32x16_bf16 v[48:63], v[160:163], v[208:211], v[48:63]
	v_exp_f32_e32 v128, v128
	v_exp_f32_e32 v129, v129
	ds_read_b64_tr_b16 v[92:93], v245 offset:32768
	ds_read_b64_tr_b16 v[94:95], v245 offset:33280
	s_waitcnt lgkmcnt(14)
	v_mfma_f32_32x32x16_bf16 v[32:47], v[160:163], v[96:99], v[32:47]
	v_exp_f32_e32 v130, v130
	v_exp_f32_e32 v131, v131
	ds_read_b64_tr_b16 v[96:97], v245 offset:36864
	ds_read_b64_tr_b16 v[98:99], v245 offset:37376
	s_waitcnt lgkmcnt(14)
	v_mfma_f32_32x32x16_bf16 v[48:63], v[156:159], v[100:103], v[48:63]
	v_exp_f32_e32 v132, v132
	v_exp_f32_e32 v133, v133
	ds_read_b64_tr_b16 v[100:101], v245 offset:33792
	ds_read_b64_tr_b16 v[102:103], v245 offset:34304
	s_waitcnt lgkmcnt(14)
	v_mfma_f32_32x32x16_bf16 v[32:47], v[156:159], v[104:107], v[32:47]
	v_exp_f32_e32 v134, v134
	v_exp_f32_e32 v135, v135
	ds_read_b64_tr_b16 v[104:105], v245 offset:37888
	ds_read_b64_tr_b16 v[106:107], v245 offset:38400
	s_waitcnt lgkmcnt(14)
	v_mfma_f32_32x32x16_bf16 v[48:63], v[148:151], v[108:111], v[48:63]
	v_exp_f32_e32 v136, v136
	v_exp_f32_e32 v137, v137
	ds_read_b64_tr_b16 v[108:109], v245 offset:34816
	ds_read_b64_tr_b16 v[110:111], v245 offset:35328
	s_waitcnt lgkmcnt(14)
	v_mfma_f32_32x32x16_bf16 v[32:47], v[148:151], v[80:83], v[32:47]
	v_exp_f32_e32 v138, v138
	v_exp_f32_e32 v139, v139
	ds_read_b64_tr_b16 v[196:197], v245 offset:38912
	ds_read_b64_tr_b16 v[198:199], v245 offset:39424
	s_waitcnt lgkmcnt(14)
	v_mfma_f32_32x32x16_bf16 v[48:63], v[144:147], v[84:87], v[48:63]
	v_exp_f32_e32 v140, v140
	v_exp_f32_e32 v141, v141
	ds_read_b64_tr_b16 v[84:85], v245 offset:35840
	ds_read_b64_tr_b16 v[86:87], v245 offset:36352
	s_waitcnt lgkmcnt(14)
	v_mfma_f32_32x32x16_bf16 v[32:47], v[144:147], v[88:91], v[32:47]
	v_exp_f32_e32 v142, v142
	v_exp_f32_e32 v143, v143
	ds_read_b64_tr_b16 v[88:89], v245 offset:39936
	ds_read_b64_tr_b16 v[90:91], v245 offset:40448
	s_waitcnt lgkmcnt(14)
	v_mfma_f32_32x32x16_bf16 v[16:31], v[160:163], v[92:95], v[16:31]
	s_add_i32 s4, s35, s71
	s_mov_b32 m0, s4
	s_nop 0
	global_load_lds_dwordx4 v248, s[98:99]
	s_lshl_b32 s4, s36, 1
	s_add_i32 s4, s4, s74
	s_mov_b32 m0, s4
	s_nop 0
	global_load_lds_dwordx4 v250, s[100:101]
	s_addk_i32 s4, 0x2000
	s_mov_b32 m0, s4
	s_nop 0
	global_load_lds_dwordx4 v252, s[100:101]
	v_exp_f32_e32 v112, v112
	v_exp_f32_e32 v113, v113
	s_waitcnt lgkmcnt(12)
	v_mfma_f32_32x32x16_bf16 v[0:15], v[160:163], v[96:99], v[0:15]
	v_exp_f32_e32 v114, v114
	v_exp_f32_e32 v115, v115
	v_add_u32_e32 v92, s36, v239
	ds_read_b128 v[80:83], v92
	ds_read_b128 v[204:207], v92 offset:512
	s_waitcnt lgkmcnt(12)
	v_mfma_f32_32x32x16_bf16 v[16:31], v[156:159], v[100:103], v[16:31]
	v_exp_f32_e32 v116, v116
	v_exp_f32_e32 v117, v117
	ds_read_b128 v[200:203], v92 offset:2048
	ds_read_b128 v[192:195], v92 offset:2560
	s_waitcnt lgkmcnt(12)
	v_mfma_f32_32x32x16_bf16 v[0:15], v[156:159], v[104:107], v[0:15]
	v_exp_f32_e32 v118, v118
	v_exp_f32_e32 v119, v119
	ds_read_b128 v[188:191], v92 offset:4096
	ds_read_b128 v[184:187], v92 offset:4608
	s_waitcnt lgkmcnt(12)
	v_mfma_f32_32x32x16_bf16 v[16:31], v[148:151], v[108:111], v[16:31]
	v_exp_f32_e32 v120, v120
	v_exp_f32_e32 v121, v121
	ds_read_b128 v[180:183], v92 offset:6144
	ds_read_b128 v[176:179], v92 offset:6656
	s_waitcnt lgkmcnt(12)
	v_mfma_f32_32x32x16_bf16 v[0:15], v[148:151], v[196:199], v[0:15]
	v_exp_f32_e32 v122, v122
	v_exp_f32_e32 v123, v123
	s_waitcnt lgkmcnt(10)
	v_mfma_f32_32x32x16_bf16 v[16:31], v[144:147], v[84:87], v[16:31]
	v_exp_f32_e32 v124, v124
	v_exp_f32_e32 v125, v125
	s_waitcnt lgkmcnt(8)
	v_mfma_f32_32x32x16_bf16 v[0:15], v[144:147], v[88:91], v[0:15]
	v_exp_f32_e32 v126, v126
	v_exp_f32_e32 v127, v127
	s_add_i32 s4, s36, 0x2000
	s_cmpk_lg_i32 s36, 0x4000
	s_cselect_b32 s75, s4, 0
	s_lshl_b32 s4, s35, 1
	v_add_u32_e32 v209, s4, v240
	s_waitcnt vmcnt(3) lgkmcnt(0)
	s_barrier
	s_andn2_b64 vcc, exec, s[10:11]
	v_add_u32_e32 v208, s49, v242
	s_cbranch_vccnz .LBB0_1362
	s_waitcnt lgkmcnt(0)
	ds_read_b128 v[84:87], v208 offset:96
	ds_read_b128 v[88:91], v208 offset:64
	ds_read_b128 v[92:95], v208 offset:32
	ds_read_b128 v[96:99], v208
	s_waitcnt lgkmcnt(3)
	v_pk_mul_f32 v[60:61], v[60:61], v[84:85]
	s_waitcnt lgkmcnt(2)
	v_pk_mul_f32 v[56:57], v[56:57], v[88:89]
	s_waitcnt lgkmcnt(1)
	v_pk_mul_f32 v[52:53], v[52:53], v[92:93]
	v_pk_mul_f32 v[62:63], v[62:63], v[86:87]
	v_pk_mul_f32 v[58:59], v[58:59], v[90:91]
	v_pk_mul_f32 v[54:55], v[54:55], v[94:95]
	s_waitcnt lgkmcnt(0)
	v_pk_mul_f32 v[50:51], v[50:51], v[98:99]
	v_pk_mul_f32 v[48:49], v[48:49], v[96:97]
	v_pk_mul_f32 v[44:45], v[44:45], v[84:85]
	v_pk_mul_f32 v[40:41], v[40:41], v[88:89]
	v_pk_mul_f32 v[36:37], v[36:37], v[92:93]
	v_pk_mul_f32 v[46:47], v[46:47], v[86:87]
	v_pk_mul_f32 v[42:43], v[42:43], v[90:91]
	v_pk_mul_f32 v[38:39], v[38:39], v[94:95]
	v_pk_mul_f32 v[34:35], v[34:35], v[98:99]
	v_pk_mul_f32 v[32:33], v[32:33], v[96:97]
	v_pk_mul_f32 v[28:29], v[28:29], v[84:85]
	v_pk_mul_f32 v[24:25], v[24:25], v[88:89]
	v_pk_mul_f32 v[20:21], v[20:21], v[92:93]
	v_pk_mul_f32 v[30:31], v[30:31], v[86:87]
	v_pk_mul_f32 v[26:27], v[26:27], v[90:91]
	v_pk_mul_f32 v[22:23], v[22:23], v[94:95]
	v_pk_mul_f32 v[18:19], v[18:19], v[98:99]
	v_pk_mul_f32 v[16:17], v[16:17], v[96:97]
	v_pk_mul_f32 v[12:13], v[12:13], v[84:85]
	v_pk_mul_f32 v[8:9], v[8:9], v[88:89]
	v_pk_mul_f32 v[4:5], v[4:5], v[92:93]
	v_pk_mul_f32 v[14:15], v[14:15], v[86:87]
	v_pk_mul_f32 v[10:11], v[10:11], v[90:91]
	v_pk_mul_f32 v[6:7], v[6:7], v[94:95]
	v_pk_mul_f32 v[2:3], v[2:3], v[98:99]
	v_pk_mul_f32 v[0:1], v[0:1], v[96:97]
.LBB0_1362:
	ds_read_b64_tr_b16 v[196:197], v209 offset:24576
	ds_read_b64_tr_b16 v[198:199], v209 offset:25088
	s_waitcnt lgkmcnt(9)
	v_mfma_f32_32x32x16_bf16 v[96:111], v[80:83], v[172:175], v[64:79]
	v_add_f32_e32 v84, v128, v129
	v_add_f32_e32 v84, v130, v84
	v_add_f32_e32 v84, v131, v84
	v_add_f32_e32 v84, v132, v84
	v_add_f32_e32 v84, v133, v84
	v_cvt_pk_bf16_f32 v160, v128, v129
	v_cvt_pk_bf16_f32 v161, v130, v131
	ds_read_b64_tr_b16 v[128:129], v209 offset:28672
	ds_read_b64_tr_b16 v[130:131], v209 offset:29184
	v_add_f32_e32 v80, v134, v84
	v_add_f32_e32 v80, v135, v80
	v_add_f32_e32 v80, v136, v80
	v_add_f32_e32 v144, v137, v80
	s_waitcnt lgkmcnt(10)
	v_mfma_f32_32x32x16_bf16 v[80:95], v[204:207], v[172:175], v[64:79]
	v_cvt_pk_bf16_f32 v162, v132, v133
	v_cvt_pk_bf16_f32 v163, v134, v135
	ds_read_b64_tr_b16 v[132:133], v209 offset:25600
	ds_read_b64_tr_b16 v[134:135], v209 offset:26112
	s_waitcnt lgkmcnt(11)
	v_mfma_f32_32x32x16_bf16 v[96:111], v[200:203], v[168:171], v[96:111]
	v_add_f32_e32 v144, v138, v144
	v_add_f32_e32 v144, v139, v144
	v_add_f32_e32 v144, v140, v144
	v_add_f32_e32 v144, v141, v144
	v_cvt_pk_bf16_f32 v156, v136, v137
	v_cvt_pk_bf16_f32 v157, v138, v139
	ds_read_b64_tr_b16 v[136:137], v209 offset:29696
	ds_read_b64_tr_b16 v[138:139], v209 offset:30208
	s_waitcnt lgkmcnt(12)
	v_mfma_f32_32x32x16_bf16 v[80:95], v[192:195], v[168:171], v[80:95]
	v_add_f32_e32 v144, v142, v144
	v_add_f32_e32 v144, v143, v144
	v_add_f32_e32 v144, v112, v144
	v_add_f32_e32 v144, v113, v144
	v_cvt_pk_bf16_f32 v158, v140, v141
	v_cvt_pk_bf16_f32 v159, v142, v143
	ds_read_b64_tr_b16 v[140:141], v209 offset:26624
	ds_read_b64_tr_b16 v[142:143], v209 offset:27136
	s_waitcnt lgkmcnt(13)
	v_mfma_f32_32x32x16_bf16 v[96:111], v[188:191], v[164:167], v[96:111]
	v_add_f32_e32 v144, v114, v144
	v_add_f32_e32 v144, v115, v144
	v_add_f32_e32 v144, v116, v144
	v_add_f32_e32 v144, v117, v144
	v_cvt_pk_bf16_f32 v148, v112, v113
	v_cvt_pk_bf16_f32 v149, v114, v115
	ds_read_b64_tr_b16 v[112:113], v209 offset:30720
	ds_read_b64_tr_b16 v[114:115], v209 offset:31232
	s_waitcnt lgkmcnt(14)
	v_mfma_f32_32x32x16_bf16 v[80:95], v[184:187], v[164:167], v[80:95]
	v_add_f32_e32 v144, v118, v144
	v_add_f32_e32 v144, v119, v144
	v_add_f32_e32 v144, v120, v144
	v_add_f32_e32 v144, v121, v144
	v_cvt_pk_bf16_f32 v150, v116, v117
	v_cvt_pk_bf16_f32 v151, v118, v119
	ds_read_b64_tr_b16 v[116:117], v209 offset:27648
	ds_read_b64_tr_b16 v[118:119], v209 offset:28160
	s_waitcnt lgkmcnt(14)
	v_mfma_f32_32x32x16_bf16 v[96:111], v[180:183], v[152:155], v[96:111]
	v_add_f32_e32 v144, v122, v144
	v_add_f32_e32 v144, v123, v144
	v_add_f32_e32 v144, v124, v144
	v_add_f32_e32 v184, v125, v144
	v_cvt_pk_bf16_f32 v144, v120, v121
	v_cvt_pk_bf16_f32 v145, v122, v123
	ds_read_b64_tr_b16 v[120:121], v209 offset:31744
	ds_read_b64_tr_b16 v[122:123], v209 offset:32256
	v_mfma_f32_32x32x16_bf16 v[80:95], v[176:179], v[152:155], v[80:95]
	v_add_f32_e32 v146, v126, v184
	v_add_f32_e32 v146, v127, v146
	v_add_f32_e32 v180, 0, v146
	v_cvt_pk_bf16_f32 v146, v124, v125
	v_cvt_pk_bf16_f32 v147, v126, v127
	v_max_f32_e32 v124, v96, v97
	s_nop 3
	s_nop 1
	v_max3_f32 v125, v98, v99, v81
	v_max3_f32 v124, v124, v80, v82
	v_max3_f32 v124, v124, v83, v100
	v_max3_f32 v125, v125, v102, v103
	v_max3_f32 v124, v124, v101, v84
	v_max3_f32 v125, v125, v86, v87
	v_max3_f32 v124, v124, v85, v104
	v_max3_f32 v125, v125, v106, v107
	v_max3_f32 v124, v124, v105, v88
	v_max3_f32 v125, v125, v90, v91
	v_max3_f32 v124, v124, v89, v108
	v_max3_f32 v125, v125, v110, v111
	v_max3_f32 v124, v124, v109, v92
	v_max3_f32 v125, v125, v94, v95
	v_max3_f32 v124, v124, v93, v125
	v_mov_b32_e32 v125, v124
	s_nop 0
	s_nop 0
	v_permlane32_swap_b32_e32 v124, v125
	v_max_f32_e32 v124, v124, v125
	v_cmp_lt_f32_e32 vcc, s41, v124
	s_cmp_lg_u64 vcc, 0
	v_add_f32_e32 v243, v233, v180
	s_cselect_b64 s[10:11], -1, 0
	s_cbranch_vccnz .LBB0_1370
.LBB0_1363:
	s_waitcnt lgkmcnt(14)
	v_mfma_f32_32x32x16_bf16 v[48:63], v[160:163], v[196:199], v[48:63]
	v_exp_f32_e32 v96, v96
	v_exp_f32_e32 v97, v97
	ds_read_b64_tr_b16 v[124:125], v209 offset:32768
	ds_read_b64_tr_b16 v[126:127], v209 offset:33280
	s_waitcnt lgkmcnt(14)
	v_mfma_f32_32x32x16_bf16 v[32:47], v[160:163], v[128:131], v[32:47]
	v_exp_f32_e32 v98, v98
	v_exp_f32_e32 v99, v99
	ds_read_b64_tr_b16 v[128:129], v209 offset:36864
	ds_read_b64_tr_b16 v[130:131], v209 offset:37376
	s_waitcnt lgkmcnt(14)
	v_mfma_f32_32x32x16_bf16 v[48:63], v[156:159], v[132:135], v[48:63]
	v_exp_f32_e32 v100, v100
	v_exp_f32_e32 v101, v101
	ds_read_b64_tr_b16 v[132:133], v209 offset:33792
	ds_read_b64_tr_b16 v[134:135], v209 offset:34304
	s_waitcnt lgkmcnt(14)
	v_mfma_f32_32x32x16_bf16 v[32:47], v[156:159], v[136:139], v[32:47]
	v_exp_f32_e32 v102, v102
	v_exp_f32_e32 v103, v103
	ds_read_b64_tr_b16 v[136:137], v209 offset:37888
	ds_read_b64_tr_b16 v[138:139], v209 offset:38400
	s_waitcnt lgkmcnt(14)
	v_mfma_f32_32x32x16_bf16 v[48:63], v[148:151], v[140:143], v[48:63]
	v_exp_f32_e32 v104, v104
	v_exp_f32_e32 v105, v105
	ds_read_b64_tr_b16 v[140:141], v209 offset:34816
	ds_read_b64_tr_b16 v[142:143], v209 offset:35328
	s_waitcnt lgkmcnt(14)
	v_mfma_f32_32x32x16_bf16 v[32:47], v[148:151], v[112:115], v[32:47]
	v_exp_f32_e32 v106, v106
	v_exp_f32_e32 v107, v107
	ds_read_b64_tr_b16 v[112:113], v209 offset:38912
	ds_read_b64_tr_b16 v[114:115], v209 offset:39424
	s_waitcnt lgkmcnt(14)
	v_mfma_f32_32x32x16_bf16 v[48:63], v[144:147], v[116:119], v[48:63]
	v_exp_f32_e32 v108, v108
	v_exp_f32_e32 v109, v109
	ds_read_b64_tr_b16 v[116:117], v209 offset:35840
	ds_read_b64_tr_b16 v[118:119], v209 offset:36352
	s_waitcnt lgkmcnt(14)
	v_mfma_f32_32x32x16_bf16 v[32:47], v[144:147], v[120:123], v[32:47]
	v_exp_f32_e32 v110, v110
	v_exp_f32_e32 v111, v111
	ds_read_b64_tr_b16 v[120:121], v209 offset:39936
	ds_read_b64_tr_b16 v[122:123], v209 offset:40448
	s_waitcnt lgkmcnt(14)
	v_mfma_f32_32x32x16_bf16 v[16:31], v[160:163], v[124:127], v[16:31]
	s_add_i32 s4, s36, s71
	s_mov_b32 m0, s4
	s_nop 0
	global_load_lds_dwordx4 v249, s[98:99]
	s_lshl_b32 s4, s75, 1
	s_add_i32 s4, s4, s74
	s_mov_b32 m0, s4
	s_nop 0
	global_load_lds_dwordx4 v251, s[100:101]
	s_addk_i32 s4, 0x2000
	s_mov_b32 m0, s4
	s_nop 0
	global_load_lds_dwordx4 v253, s[100:101]
	v_exp_f32_e32 v80, v80
	v_exp_f32_e32 v81, v81
	s_waitcnt lgkmcnt(12)
	v_mfma_f32_32x32x16_bf16 v[0:15], v[160:163], v[128:131], v[0:15]
	v_exp_f32_e32 v82, v82
	v_exp_f32_e32 v83, v83
	v_add_u32_e32 v124, s75, v239
	ds_read_b128 v[204:207], v124
	ds_read_b128 v[200:203], v124 offset:512
	s_waitcnt lgkmcnt(12)
	v_mfma_f32_32x32x16_bf16 v[16:31], v[156:159], v[132:135], v[16:31]
	v_exp_f32_e32 v84, v84
	v_exp_f32_e32 v85, v85
	ds_read_b128 v[196:199], v124 offset:2048
	ds_read_b128 v[192:195], v124 offset:2560
	s_waitcnt lgkmcnt(12)
	v_mfma_f32_32x32x16_bf16 v[0:15], v[156:159], v[136:139], v[0:15]
	v_exp_f32_e32 v86, v86
	v_exp_f32_e32 v87, v87
	ds_read_b128 v[188:191], v124 offset:4096
	ds_read_b128 v[184:187], v124 offset:4608
	s_waitcnt lgkmcnt(12)
	v_mfma_f32_32x32x16_bf16 v[16:31], v[148:151], v[140:143], v[16:31]
	v_exp_f32_e32 v88, v88
	v_exp_f32_e32 v89, v89
	ds_read_b128 v[180:183], v124 offset:6144
	ds_read_b128 v[176:179], v124 offset:6656
	s_waitcnt lgkmcnt(12)
	v_mfma_f32_32x32x16_bf16 v[0:15], v[148:151], v[112:115], v[0:15]
	v_exp_f32_e32 v90, v90
	v_exp_f32_e32 v91, v91
	s_waitcnt lgkmcnt(10)
	v_mfma_f32_32x32x16_bf16 v[16:31], v[144:147], v[116:119], v[16:31]
	v_exp_f32_e32 v92, v92
	v_exp_f32_e32 v93, v93
	s_waitcnt lgkmcnt(8)
	v_mfma_f32_32x32x16_bf16 v[0:15], v[144:147], v[120:123], v[0:15]
	v_exp_f32_e32 v94, v94
	v_exp_f32_e32 v95, v95
	s_add_i32 s34, s34, 2
	s_add_i32 s4, s75, 0x2000
	s_cmpk_lg_i32 s75, 0x4000
	s_cselect_b32 s76, s4, 0
	s_add_u32 s98, s98, s16
	s_addc_u32 s99, s99, s17
	s_add_u32 s100, s100, s16
	s_addc_u32 s101, s101, s17
	s_lshl_b32 s4, s36, 1
	v_add_u32_e32 v245, s4, v240
	s_waitcnt vmcnt(3) lgkmcnt(0)
	s_barrier
	s_andn2_b64 vcc, exec, s[10:11]
	s_cbranch_vccnz .LBB0_1365
	s_waitcnt lgkmcnt(0)
	ds_read_b128 v[112:115], v208 offset:96
	ds_read_b128 v[116:119], v208 offset:64
	ds_read_b128 v[120:123], v208 offset:32
	ds_read_b128 v[124:127], v208
	s_waitcnt lgkmcnt(3)
	v_pk_mul_f32 v[60:61], v[60:61], v[112:113]
	s_waitcnt lgkmcnt(2)
	v_pk_mul_f32 v[56:57], v[56:57], v[116:117]
	s_waitcnt lgkmcnt(1)
	v_pk_mul_f32 v[52:53], v[52:53], v[120:121]
	v_pk_mul_f32 v[62:63], v[62:63], v[114:115]
	v_pk_mul_f32 v[58:59], v[58:59], v[118:119]
	v_pk_mul_f32 v[54:55], v[54:55], v[122:123]
	s_waitcnt lgkmcnt(0)
	v_pk_mul_f32 v[50:51], v[50:51], v[126:127]
	v_pk_mul_f32 v[48:49], v[48:49], v[124:125]
	v_pk_mul_f32 v[44:45], v[44:45], v[112:113]
	v_pk_mul_f32 v[40:41], v[40:41], v[116:117]
	v_pk_mul_f32 v[36:37], v[36:37], v[120:121]
	v_pk_mul_f32 v[46:47], v[46:47], v[114:115]
	v_pk_mul_f32 v[42:43], v[42:43], v[118:119]
	v_pk_mul_f32 v[38:39], v[38:39], v[122:123]
	v_pk_mul_f32 v[34:35], v[34:35], v[126:127]
	v_pk_mul_f32 v[32:33], v[32:33], v[124:125]
	v_pk_mul_f32 v[28:29], v[28:29], v[112:113]
	v_pk_mul_f32 v[24:25], v[24:25], v[116:117]
	v_pk_mul_f32 v[20:21], v[20:21], v[120:121]
	v_pk_mul_f32 v[30:31], v[30:31], v[114:115]
	v_pk_mul_f32 v[26:27], v[26:27], v[118:119]
	v_pk_mul_f32 v[22:23], v[22:23], v[122:123]
	v_pk_mul_f32 v[18:19], v[18:19], v[126:127]
	v_pk_mul_f32 v[16:17], v[16:17], v[124:125]
	v_pk_mul_f32 v[12:13], v[12:13], v[112:113]
	v_pk_mul_f32 v[8:9], v[8:9], v[116:117]
	v_pk_mul_f32 v[4:5], v[4:5], v[120:121]
	v_pk_mul_f32 v[14:15], v[14:15], v[114:115]
	v_pk_mul_f32 v[10:11], v[10:11], v[118:119]
	v_pk_mul_f32 v[6:7], v[6:7], v[122:123]
	v_pk_mul_f32 v[2:3], v[2:3], v[126:127]
	v_pk_mul_f32 v[0:1], v[0:1], v[124:125]
